# team stagger with panel_index x s_sleep 1 (about 2 us total spread)
# speedup vs baseline: 1.0015x; 1.0015x over previous
.Lstag_loop:
	s_cmp_eq_u32 s96, 0
	s_cbranch_scc1 .Lstag_done
	s_sleep 1
	s_sub_u32 s96, s96, 1
	s_branch .Lstag_loop
